# last layer's norm_rows remapped to the row block too; P8|P9 is a row-block seam in every layer
# speedup vs baseline: 1.0061x; 1.0061x over previous
; #define LAS __attribute__((address_space(3)))
; __global__ void __launch_bounds__(NTHR, 2) fwd(Args args) {
;     extern __shared__ __attribute__((aligned(16))) unsigned char lds_raw[];
;     LAS unsigned char* lds = (LAS unsigned char*)lds_raw;
;     volatile LAS int* MISC = (volatile LAS int*)(lds + MISC_OFF);
;     const int G = gridDim.x, NGW = G * NWAVES;
;     ...
;     const int lo = args.ph_lo, hi = args.ph_hi;
;     if (threadIdx.x < 64) MISC[threadIdx.x] = 0;
;     __syncthreads();
;     XcdBarrier bar = xcd_barrier_post(ctl + CW_BAR, (volatile LAS unsigned*)(MISC + 8));
;     int ph = 0;
.LBB0_124:
	s_cmpk_lt_i32 s2, 0x640
	s_cselect_b64 s[4:5], -1, 0
	v_writelane_b32 v254, s4, 2
	s_ashr_i32 s33, s2, 31
	s_ashr_i32 s60, s3, 31
	v_writelane_b32 v254, s5, 3
	s_lshr_b32 s4, s33, 29
	s_add_i32 s5, s2, s4
	s_ashr_i32 s4, s5, 3
	s_and_b32 s5, s5, -8
	s_sub_i32 s5, s2, s5
	s_add_u32 s6, s8, 0x8200
	s_addc_u32 s7, s9, 0
	s_add_u32 s76, s8, 0x8400
	s_addc_u32 s77, s9, 0
	s_add_u32 s78, s8, 0x8500
	v_writelane_b32 v254, s6, 4
	s_addc_u32 s79, s9, 0
	s_mov_b32 s16, 0x41c00000
	v_writelane_b32 v254, s7, 5
	s_add_u32 s6, s8, 0x8600
	s_addc_u32 s7, s9, 0
	v_writelane_b32 v254, s6, 6
	s_mov_b32 s18, 0x41d00000
	v_mbcnt_lo_u32_b32 v0, -1, 0
	v_writelane_b32 v254, s7, 7
	s_add_u32 s6, s8, 0x8700
	s_addc_u32 s7, s9, 0
	v_writelane_b32 v254, s6, 8
	v_mov_b32_e32 v1, 0
	v_mov_b32_e32 v224, 1
	v_writelane_b32 v254, s7, 9
	s_add_u32 s6, s8, 0x8800
	s_addc_u32 s7, s9, 0
	v_writelane_b32 v254, s6, 10
	v_mov_b32_e32 v234, 0x260
	v_mov_b32_e32 v235, 0x3c23d70a
	v_writelane_b32 v254, s7, 11
	s_add_u32 s6, s8, 0x8900
	s_addc_u32 s7, s9, 0
	v_writelane_b32 v254, s6, 12
	s_mov_b32 s17, 0x41c80000
	s_mov_b32 s19, 0x41d80000
	v_writelane_b32 v254, s7, 13
	s_add_u32 s6, s8, 0x8a00
	s_addc_u32 s7, s9, 0
	v_writelane_b32 v254, s6, 14
	v_mov_b32_e32 v236, 0x358637bd
	v_mov_b64_e32 v[226:227], 0x600
	v_writelane_b32 v254, s7, 15
	s_add_u32 s6, s8, 0x8b00
	s_addc_u32 s7, s9, 0
	v_writelane_b32 v254, s6, 16
	v_mov_b64_e32 v[228:229], 0x5ff
	v_mov_b32_e32 v225, 0x3e38aa3b
	v_writelane_b32 v254, s7, 17
	s_add_u32 s6, s8, 0x8c00
	s_addc_u32 s7, s9, 0
	v_writelane_b32 v254, s6, 18
	v_mov_b32_e32 v230, 0x3db504f3
	v_mbcnt_hi_u32_b32 v240, -1, v0
	v_writelane_b32 v254, s7, 19
	s_add_u32 s6, s8, 0x8d00
	s_addc_u32 s7, s9, 0
	v_writelane_b32 v254, s6, 20
	v_mov_b32_e32 v241, 0x42800000
	v_mov_b32_e32 v242, 0x42000000
	v_writelane_b32 v254, s7, 21
	s_add_u32 s6, s8, 0x8e00
	s_addc_u32 s7, s9, 0
	v_writelane_b32 v254, s6, 22
	v_mov_b32_e32 v243, 0x3fb8aa3b
	v_mov_b32_e32 v244, 0xff800000
	v_writelane_b32 v254, s7, 23
	s_add_u32 s6, s8, 0x8f00
	s_addc_u32 s7, s9, 0
	v_writelane_b32 v254, s6, 24
	v_mov_b32_e32 v245, 0xc8000
	v_mov_b64_e32 v[212:213], 0x200
	v_writelane_b32 v254, s7, 25
	s_add_u32 s6, s8, 0x9000
	s_addc_u32 s7, s9, 0
	v_writelane_b32 v254, s6, 26
	v_mov_b64_e32 v[214:215], 0x1ff
	v_mov_b64_e32 v[238:239], 0xb00
	v_writelane_b32 v254, s7, 27
	s_add_u32 s6, s8, 0x9100
	s_addc_u32 s7, s9, 0
	v_writelane_b32 v254, s6, 28
	v_mov_b64_e32 v[218:219], 0xaff
	s_movk_i32 s61, 0x3200
	v_writelane_b32 v254, s7, 29
	s_add_u32 s6, s8, 0x9200
	s_addc_u32 s7, s9, 0
	v_writelane_b32 v254, s6, 30
	s_movk_i32 s62, 0x1000
	s_mov_b32 s64, 0xc2fc0000
	v_writelane_b32 v254, s7, 31
	s_add_u32 s6, s8, 0x9300
	s_addc_u32 s7, s9, 0
	v_writelane_b32 v254, s6, 32
	s_cmp_eq_u32 s52, 15
	s_movk_i32 s65, 0x110
	v_writelane_b32 v254, s7, 33
	s_cselect_b64 s[6:7], -1, 0
	v_writelane_b32 v254, s6, 34
	s_cmp_eq_u32 s52, 14
	s_movk_i32 s66, 0x600
	v_writelane_b32 v254, s7, 35
	s_cselect_b64 s[6:7], -1, 0
	v_writelane_b32 v254, s6, 36
	s_cmp_eq_u32 s52, 13
	s_mov_b32 s67, 0x40c00000
	v_writelane_b32 v254, s7, 37
	s_cselect_b64 s[6:7], -1, 0
	v_writelane_b32 v254, s6, 38
	s_cmp_eq_u32 s52, 12
	s_mov_b32 s68, 0xf800000
	v_writelane_b32 v254, s7, 39
	s_cselect_b64 s[6:7], -1, 0
	v_writelane_b32 v254, s6, 40
	s_cmp_eq_u32 s52, 11
	s_mov_b32 s69, 0x42a00000
	v_writelane_b32 v254, s7, 41
	s_cselect_b64 s[6:7], -1, 0
	v_writelane_b32 v254, s6, 42
	s_cmp_eq_u32 s52, 10
	s_movk_i32 s71, 0x7fff
	v_writelane_b32 v254, s7, 43
	s_cselect_b64 s[6:7], -1, 0
	v_writelane_b32 v254, s6, 44
	s_cmp_eq_u32 s52, 9
	s_mov_b32 s72, 0x5040100
	v_writelane_b32 v254, s7, 45
	s_cselect_b64 s[6:7], -1, 0
	v_writelane_b32 v254, s6, 46
	s_cmp_eq_u32 s52, 8
	s_movk_i32 s73, 0x2c00
	v_writelane_b32 v254, s7, 47
	s_cselect_b64 s[6:7], -1, 0
	v_writelane_b32 v254, s6, 48
	s_cmp_eq_u32 s52, 7
	s_mov_b32 s21, 0
	v_writelane_b32 v254, s7, 49
	s_cselect_b64 s[6:7], -1, 0
	v_writelane_b32 v254, s6, 50
	s_cmp_eq_u32 s52, 6
	s_mov_b64 s[30:31], 0x80
	v_writelane_b32 v254, s7, 51
	s_cselect_b64 s[6:7], -1, 0
	v_writelane_b32 v254, s6, 52
	s_cmp_eq_u32 s52, 5
	s_nop 0
	v_writelane_b32 v254, s7, 53
	s_cselect_b64 s[6:7], -1, 0
	v_writelane_b32 v254, s6, 54
	s_cmp_eq_u32 s52, 4
	s_nop 0
	v_writelane_b32 v254, s7, 55
	s_cselect_b64 s[6:7], -1, 0
	v_writelane_b32 v254, s6, 56
	s_cmp_eq_u32 s52, 3
	s_nop 0
	v_writelane_b32 v254, s7, 57
	s_cselect_b64 s[6:7], -1, 0
	v_writelane_b32 v254, s6, 58
	s_cmp_eq_u32 s52, 2
	s_nop 0
	v_writelane_b32 v254, s7, 59
	s_cselect_b64 s[6:7], -1, 0
	v_writelane_b32 v254, s6, 60
	s_cmp_eq_u32 s52, 1
	s_nop 0
	v_writelane_b32 v254, s7, 61
	s_cselect_b64 s[6:7], -1, 0
	v_writelane_b32 v254, s6, 62
	s_cmp_eq_u32 s52, 0
	s_nop 0
	v_writelane_b32 v254, s7, 63
; #define LAS __attribute__((address_space(3)))
; __global__ void __launch_bounds__(NTHR, 2) fwd(Args args) {
;     extern __shared__ __attribute__((aligned(16))) unsigned char lds_raw[];
;     LAS unsigned char* lds = (LAS unsigned char*)lds_raw;
;     volatile LAS int* MISC = (volatile LAS int*)(lds + MISC_OFF);
;     const int G = gridDim.x, NGW = G * NWAVES;
;     ...
;     const int lo = args.ph_lo, hi = args.ph_hi;
;     if (threadIdx.x < 64) MISC[threadIdx.x] = 0;
;     __syncthreads();
;     XcdBarrier bar = xcd_barrier_post(ctl + CW_BAR, (volatile LAS unsigned*)(MISC + 8));
;     int ph = 0;
	s_cselect_b64 s[6:7], -1, 0
	v_writelane_b32 v255, s6, 0
	s_nop 1
	v_writelane_b32 v255, s7, 1
	s_lshl_b32 s6, s52, 8
	s_add_u32 s6, s10, s6
	s_addc_u32 s7, s11, 0
	s_add_u32 s10, s6, 0x1400
	s_addc_u32 s11, s7, 0
	v_writelane_b32 v255, s10, 2
	s_add_u32 s6, s6, 0x2400
	s_addc_u32 s7, s7, 0
	v_writelane_b32 v255, s11, 3
	v_writelane_b32 v255, s6, 4
	s_nop 1
	v_writelane_b32 v255, s7, 5
	s_add_u32 s6, s8, 0xb400
	s_addc_u32 s7, s9, 0
	v_writelane_b32 v255, s6, 6
	s_nop 1
	v_writelane_b32 v255, s7, 7
	s_add_u32 s6, s8, 0xb500
	s_addc_u32 s7, s9, 0
	v_writelane_b32 v255, s6, 8
	s_lshl_b32 s20, s2, 3
	s_lshl_b32 s22, s3, 4
	v_writelane_b32 v255, s7, 9
	s_lshl_b32 s6, s2, 4
	s_cmpk_lt_i32 s2, 0x200
	v_writelane_b32 v255, s6, 10
	s_cselect_b64 s[6:7], -1, 0
	v_writelane_b32 v255, s6, 11
	s_nop 1
	v_writelane_b32 v255, s7, 12
	s_lshl_b32 s6, s5, 6
	s_cmpk_lt_i32 s2, 0xb00
	s_cselect_b64 s[8:9], -1, 0
	s_cmp_lt_i32 s5, 0
	s_mul_i32 s7, s5, 0x41
	s_cselect_b32 s6, s7, s6
	s_movk_i32 s7, 0xc9
	v_writelane_b32 v255, s8, 13
	s_cselect_b32 s7, s7, 0xc8
	s_mul_i32 s7, s5, s7
	v_writelane_b32 v255, s9, 14
	s_movk_i32 s8, 0x161
	s_cselect_b32 s8, s8, 0x160
	s_add_i32 s7, s7, s4
	s_mul_hi_i32 s9, s7, 0x51eb851f
	s_lshr_b32 s10, s9, 31
	s_ashr_i32 s9, s9, 6
	s_add_i32 s9, s9, s10
	s_mul_i32 s10, s9, 0xc8
	s_sub_i32 s7, s7, s10
	s_bfe_u32 s10, s7, 0x3001c
	s_add_i32 s10, s7, s10
	s_and_b32 s11, s10, 0xfff8
	s_add_i32 s6, s6, s4
	s_sub_i32 s7, s7, s11
	s_ashr_i32 s11, s6, 31
	s_lshr_b32 s11, s11, 26
	s_mul_i32 s5, s5, s8
	s_add_i32 s11, s6, s11
	s_add_i32 s5, s5, s4
	s_and_b32 s12, s11, 0xffc0
	s_mul_hi_i32 s4, s5, 0x2e8ba2e9
	s_sub_i32 s6, s6, s12
	s_lshr_b32 s8, s4, 31
	s_ashr_i32 s4, s4, 6
	s_bfe_i32 s12, s6, 0x80000
	s_add_i32 s8, s4, s8
	s_bfe_u32 s12, s12, 0x3000c
	s_mul_i32 s4, s8, 0x160
	s_add_i32 s12, s6, s12
	s_sub_i32 s4, s5, s4
	s_and_b32 s13, s12, 0xf8
	s_bfe_u32 s5, s4, 0x3001c
	s_sub_i32 s6, s6, s13
	s_add_i32 s13, s4, s5
	s_and_b32 s5, s13, 0xfff8
	s_sub_i32 s14, s4, s5
	s_lshl_b32 s4, s9, 3
	s_sext_i32_i16 s5, s10
	s_sext_i32_i16 s7, s7
	s_add_i32 s24, s4, s7
	s_ashr_i32 s4, s5, 3
	v_writelane_b32 v255, s4, 15
	s_lshr_b32 s4, s5, 3
	s_bfe_i64 s[4:5], s[4:5], 0x100000
	s_lshl_b64 s[4:5], s[4:5], 20
	v_writelane_b32 v255, s4, 16
	s_sext_i32_i8 s6, s6
	s_ashr_i32 s25, s24, 31
	v_writelane_b32 v255, s5, 17
	s_ashr_i32 s4, s11, 6
	s_bfe_i32 s5, s12, 0x80000
	s_lshl_b32 s4, s4, 3
	s_sext_i32_i16 s5, s5
	s_add_i32 s26, s4, s6
	s_ashr_i32 s4, s5, 3
	v_writelane_b32 v255, s4, 18
	s_lshr_b32 s4, s5, 3
	s_bfe_i64 s[4:5], s[4:5], 0x100000
	s_lshl_b64 s[4:5], s[4:5], 20
	v_writelane_b32 v255, s4, 19
	s_sext_i32_i16 s6, s14
	s_ashr_i32 s27, s26, 31
	v_writelane_b32 v255, s5, 20
	s_lshl_b32 s4, s8, 3
	s_sext_i32_i16 s5, s13
	s_add_i32 s28, s4, s6
	s_ashr_i32 s4, s5, 3
	v_writelane_b32 v255, s4, 21
	s_lshr_b32 s4, s5, 3
	s_bfe_i64 s[4:5], s[4:5], 0x100000
	s_lshl_b64 s[4:5], s[4:5], 20
	v_writelane_b32 v255, s4, 22
	s_ashr_i32 s29, s28, 31
	s_ashr_i32 s55, s54, 31
	v_writelane_b32 v255, s5, 23
	s_mov_b32 s4, 1
	v_writelane_b32 v255, s4, 24
	v_writelane_b32 v255, s20, 25
	s_add_i32 s4, s20, s54
	v_writelane_b32 v255, s4, 26
	s_add_i32 s4, 0, 0x22020
	v_writelane_b32 v255, s4, 27
	s_add_i32 s4, 0, 0x22024
	v_writelane_b32 v255, s4, 28
	s_add_i32 s4, 0, 0x19800
	v_writelane_b32 v255, s4, 29
	s_mov_b32 s4, 0
	v_writelane_b32 v255, s4, 30
	s_mov_b32 s4, s24
	v_writelane_b32 v255, s4, 31
	s_mov_b32 s6, 2.0
	s_mov_b32 s8, 0x41000000
	v_writelane_b32 v255, s5, 32
	s_lshl_b64 s[4:5], s[24:25], 20
	v_writelane_b32 v255, s4, 33
	s_lshl_b64 s[24:25], s[54:55], 12
	s_mov_b32 s10, 0x41200000
	v_writelane_b32 v255, s5, 34
	s_mov_b32 s4, s26
	v_writelane_b32 v255, s4, 35
	s_mov_b32 s12, 0x41800000
	s_mov_b32 s14, 0x41900000
	v_writelane_b32 v255, s5, 36
	s_lshl_b64 s[4:5], s[26:27], 20
	v_writelane_b32 v255, s4, 37
	s_lshl_b32 s91, s3, 11
	s_mov_b32 s7, 0x40400000
	v_writelane_b32 v255, s5, 38
	s_mov_b32 s4, s28
	v_writelane_b32 v255, s4, 39
	s_mov_b32 s9, 0x41100000
	s_mov_b32 s11, 0x41300000
	v_writelane_b32 v255, s5, 40
	s_lshl_b64 s[4:5], s[28:29], 20
	v_writelane_b32 v255, s4, 41
	s_mov_b32 s13, 0x41880000
	s_mov_b32 s15, 0x41980000
	v_writelane_b32 v255, s5, 42
	s_lshl_b64 s[4:5], s[54:55], 2
	v_writelane_b32 v255, s4, 43
	s_add_i32 s63, 0, 0x22000
	s_add_i32 s70, 0, 0x11000
	v_writelane_b32 v255, s5, 44
	s_mov_b64 s[4:5], 0x40000
	v_writelane_b32 v255, s4, 45
	s_mov_b32 s55, s22
	s_mov_b64 s[28:29], 0x80000
	v_writelane_b32 v255, s5, 46
	v_writelane_b32 v255, s74, 47
	s_nop 1
	v_writelane_b32 v255, s75, 48
	v_writelane_b32 v255, s76, 49
	s_nop 1
	v_writelane_b32 v255, s77, 50
	v_writelane_b32 v255, s78, 51
	s_nop 1
	v_writelane_b32 v255, s79, 52
	v_writelane_b32 v255, s55, 53
	v_writelane_b32 v255, s91, 54
	s_branch .LBB0_128

; __device__ __forceinline__ unsigned xb_add(unsigned* p, unsigned v) { return __hip_atomic_fetch_add(p, v, __ATOMIC_RELAXED, __HIP_MEMORY_SCOPE_AGENT); }
; __device__ __forceinline__ void xcd_barrier(const XcdBarrier& b) {
;     asm volatile("s_waitcnt vmcnt(0)" ::: "memory");
;     __syncthreads();
;     if (threadIdx.x == 0) {
;         unsigned* bar = b.bar;
;         __builtin_amdgcn_s_waitcnt(0);
;         unsigned nloc = b.st[0], nx = b.st[1];
;         if (nloc == 0u) { xcd_barrier_complete(bar, b.x, nloc, nx); b.st[0] = nloc; b.st[1] = nx; }
;         const unsigned old = xb_add(&bar[XB_XSUB(b.x)], 1u);
.LBB0_790:
	v_readlane_b32 s20, v255, 24
	s_add_i32 s20, s20, 7
	s_waitcnt lgkmcnt(0)
	s_cmp_lt_i32 s20, s59
	s_cselect_b64 s[26:27], -1, 0
	s_and_b64 s[4:5], s[4:5], s[26:27]
	s_andn2_b64 vcc, exec, s[4:5]
	s_cbranch_vccnz .LBB0_844
	s_waitcnt vmcnt(0)
	s_waitcnt vmcnt(0)
	s_barrier
	s_and_saveexec_b64 s[4:5], s[74:75]
	s_cbranch_execz .LBB0_843
	s_cmp_lg_u32 s100, 0
	s_cbranch_scc1 .Lgs_known_21762
	v_readlane_b32 s22, v255, 6
	v_readlane_b32 s23, v255, 7
	s_nop 4
	global_load_dword v6, v1, s[22:23] offset:1024 sc1
	global_load_dword v7, v1, s[22:23] offset:1088 sc1
	global_load_dword v8, v1, s[22:23] offset:1152 sc1
	global_load_dword v9, v1, s[22:23] offset:1216 sc1
	global_load_dword v10, v1, s[22:23] offset:1280 sc1
	global_load_dword v11, v1, s[22:23] offset:1344 sc1
	global_load_dword v12, v1, s[22:23] offset:1408 sc1
	global_load_dword v13, v1, s[22:23] offset:1472 sc1
	s_waitcnt vmcnt(0)
	v_add_u32_e32 v14, -1, v6
	v_and_b32_e32 v14, v14, v6
	v_add_u32_e32 v15, -1, v7
	v_and_b32_e32 v15, v15, v7
	v_or_b32_e32 v14, v14, v15
	v_add_u32_e32 v15, -1, v8
	v_and_b32_e32 v15, v15, v8
	v_or_b32_e32 v14, v14, v15
	v_add_u32_e32 v15, -1, v9
	v_and_b32_e32 v15, v15, v9
	v_or_b32_e32 v14, v14, v15
	v_add_u32_e32 v15, -1, v10
	v_and_b32_e32 v15, v15, v10
	v_or_b32_e32 v14, v14, v15
	v_add_u32_e32 v15, -1, v11
	v_and_b32_e32 v15, v15, v11
	v_or_b32_e32 v14, v14, v15
	v_add_u32_e32 v15, -1, v12
	v_and_b32_e32 v15, v15, v12
	v_or_b32_e32 v14, v14, v15
	v_add_u32_e32 v15, -1, v13
	v_and_b32_e32 v15, v15, v13
	v_or_b32_e32 v14, v14, v15
	s_nop 0
	v_readfirstlane_b32 s22, v14
	s_cmp_eq_u32 s22, 0
	s_cselect_b32 s100, 1, 2
.Lgs_known_21762:
	s_cmp_eq_u32 s100, 1
	s_cbranch_scc0 .Lgs_full_21762
	s_waitcnt vmcnt(0) lgkmcnt(0)
	v_readlane_b32 s22, v255, 6
	v_readlane_b32 s23, v255, 7
	s_and_b32 s36, s2, 7
	s_lshl_b32 s36, s36, 3
	s_bfe_u32 s37, s2, 0x30003
	s_add_i32 s36, s36, s37
	s_lshl_b32 s36, s36, 6
	s_addk_i32 s36, 0x800
	v_mov_b32_e32 v6, s36
	v_mov_b32_e32 v7, 1
	s_add_i32 s101, s101, 4
	global_atomic_add v6, v7, s[22:23]
	s_mov_b32 s36, 0

; template <bool FINAL, bool DUMMY = false> __device__ __forceinline__ void norm_rows(const bfu* F, bfu* XB, const float* g1, float* RS, float* xout, int gw, int NGW, int lane, bfu* dummy = nullptr) {
;     int m = gw; if (m >= M) return;
;     v4u fw[4], xw[4];
; #pragma unroll
;     for (int j = 0; j < 4; ++j) { fw[j] = __builtin_nontemporal_load((const v4u*)(F + (size_t)m * DM) + lane + 64 * j); xw[j] = ((const v4u*)(XB + (size_t)m * DM) + lane)[64 * j]; }
;     for (; m < M; m += NGW) {
;         f32x4 f[8], x[8]; float s = 0.f;
; #pragma unroll
;         for (int j = 0; j < 4; ++j) {
;             f[2 * j] = (f32x4){bflo(fw[j].x), bfhi(fw[j].x), bflo(fw[j].y), bfhi(fw[j].y)}; f[2 * j + 1] = (f32x4){bflo(fw[j].z), bfhi(fw[j].z), bflo(fw[j].w), bfhi(fw[j].w)};
;             x[2 * j] = (f32x4){bflo(xw[j].x), bfhi(xw[j].x), bflo(xw[j].y), bfhi(xw[j].y)}; x[2 * j + 1] = (f32x4){bflo(xw[j].z), bfhi(xw[j].z), bflo(xw[j].w), bfhi(xw[j].w)}; }
;         const int mn = m + NGW;
;         if (mn < M) {
; #pragma unroll
;             for (int j = 0; j < 4; ++j) { fw[j] = __builtin_nontemporal_load((const v4u*)(F + (size_t)mn * DM) + lane + 64 * j); xw[j] = ((const v4u*)(XB + (size_t)mn * DM) + lane)[64 * j]; }
;         }
.LBB0_854:
	s_andn2_b64 vcc, exec, s[34:35]
	s_cbranch_vccnz .LBB0_860
	s_mov_b32 s40, 21
	s_mov_b32 s38, 21
	s_mov_b32 s36, 19
	s_mov_b32 s34, 20
	s_cmpk_gt_i32 s26, 0x3fff
	s_cbranch_scc1 .LBB0_860
	s_ashr_i32 s41, s40, 31
	s_lshl_b64 s[22:23], s[40:41], 3
	s_add_u32 s22, s0, s22
	s_addc_u32 s23, s1, s23
	s_ashr_i32 s39, s38, 31
	s_lshl_b64 s[38:39], s[38:39], 3
	s_add_u32 s38, s0, s38
	s_addc_u32 s39, s1, s39
	s_ashr_i32 s37, s36, 31
	s_lshl_b64 s[36:37], s[36:37], 3
	s_add_u32 s40, s0, s36
	s_addc_u32 s41, s1, s37
	s_ashr_i32 s35, s34, 31
	s_lshl_b64 s[34:35], s[34:35], 3
	s_add_u32 s42, s0, s34
	s_addc_u32 s43, s1, s35
	s_load_dwordx2 s[34:35], s[22:23], 0x0
	s_load_dwordx2 s[36:37], s[38:39], 0x0
	s_nop 0
	s_load_dwordx2 s[22:23], s[40:41], 0x0
	s_load_dwordx2 s[38:39], s[42:43], 0x0
	s_ashr_i32 s27, s26, 31
	s_lshl_b64 s[40:41], s[26:27], 12
	s_waitcnt lgkmcnt(0)
	s_add_u32 s42, s36, s40
	s_addc_u32 s43, s37, s41
	v_lshlrev_b32_e32 v0, 4, v116
	v_lshl_add_u64 v[2:3], s[42:43], 0, v[0:1]
	s_mov_b64 s[42:43], 0x18e00000
	s_add_u32 s40, s34, s40
	s_mov_b32 s20, 0x18e00000
	v_lshl_add_u64 v[4:5], v[2:3], 0, s[42:43]
	s_addc_u32 s41, s35, s41
	v_add_co_u32_e32 v2, vcc, s20, v2
	v_lshl_add_u64 v[6:7], s[40:41], 0, v[0:1]
	s_nop 0
	v_addc_co_u32_e32 v3, vcc, 0, v3, vcc
	s_mov_b32 s20, 0x2d600000
	global_load_dwordx4 v[34:37], v[4:5], off offset:3072
	global_load_dwordx4 v[42:45], v[4:5], off offset:2048
	global_load_dwordx4 v[50:53], v[4:5], off offset:1024
	global_load_dwordx4 v[58:61], v[2:3], off
	v_add_co_u32_e32 v2, vcc, s20, v6
	s_mov_b64 s[40:41], 0x2d600000
	s_nop 0
	v_addc_co_u32_e32 v3, vcc, 0, v7, vcc
	v_lshl_add_u64 v[8:9], v[6:7], 0, s[40:41]
	global_load_dwordx4 v[62:65], v[2:3], off nt
	global_load_dwordx4 v[54:57], v[8:9], off offset:1024 nt
	global_load_dwordx4 v[46:49], v[8:9], off offset:2048 nt
	global_load_dwordx4 v[38:41], v[8:9], off offset:3072 nt
	v_and_b32_e32 v4, 64, v240
	v_xor_b32_e32 v5, 1, v240
	v_add_u32_e32 v4, 64, v4
	v_xor_b32_e32 v6, 2, v240
	v_cmp_lt_i32_e32 vcc, v5, v4
	v_xor_b32_e32 v7, 4, v240
	v_xor_b32_e32 v8, 8, v240
	v_cndmask_b32_e32 v5, v240, v5, vcc
	v_cmp_lt_i32_e32 vcc, v6, v4
	v_xor_b32_e32 v9, 16, v240
	v_xor_b32_e32 v10, 32, v240
	v_cndmask_b32_e32 v6, v240, v6, vcc
	v_cmp_lt_i32_e32 vcc, v7, v4
	v_lshlrev_b32_e32 v2, 5, v116
	v_mov_b32_e32 v3, v1
	v_cndmask_b32_e32 v7, v240, v7, vcc
	v_cmp_lt_i32_e32 vcc, v8, v4
	v_lshlrev_b32_e32 v91, 2, v5
	s_sub_i32 s20, s26, s48
	s_addk_i32 s20, 0x20
	v_cndmask_b32_e32 v8, v240, v8, vcc
	v_cmp_lt_i32_e32 vcc, v9, v4
	v_lshlrev_b32_e32 v124, 2, v6
	v_lshlrev_b32_e32 v125, 2, v7
	v_cndmask_b32_e32 v9, v240, v9, vcc
	v_cmp_lt_i32_e32 vcc, v10, v4
	v_lshlrev_b32_e32 v126, 2, v8
	v_lshlrev_b32_e32 v127, 2, v9
	v_cndmask_b32_e32 v4, v240, v10, vcc
	v_lshlrev_b32_e32 v128, 2, v4
	v_lshl_add_u64 v[4:5], s[22:23], 0, v[2:3]
	s_mov_b64 s[22:23], 0x6000
	v_lshl_add_u64 v[66:67], v[4:5], 0, s[22:23]
	s_mov_b64 s[22:23], 0x7000
	v_lshl_add_u64 v[68:69], v[4:5], 0, s[22:23]
	s_mov_b64 s[22:23], 0x7800
	v_lshl_add_u64 v[70:71], v[4:5], 0, s[22:23]
	s_lshl_b64 s[22:23], s[26:27], 13
	s_and_b32 s26, s26, 0x7ff
	s_add_u32 s22, s38, s22
	s_addc_u32 s23, s39, s23
	s_add_i32 s38, s20, s48
	v_lshl_add_u64 v[2:3], s[22:23], 0, v[2:3]
	s_ashr_i32 s39, s38, 31
	s_mov_b64 s[22:23], 0x1000
	v_lshl_add_u64 v[72:73], v[2:3], 0, s[22:23]
	s_lshl_b64 s[22:23], s[38:39], 12
	s_add_u32 s36, s36, s22
	s_addc_u32 s37, s37, s23
	s_add_u32 s40, s34, s22
	s_addc_u32 s41, s35, s23
	s_waitcnt vmcnt(0)
	v_mov_b64_e32 v[18:19], v[42:43]
	v_mov_b64_e32 v[10:11], v[50:51]
	v_mov_b64_e32 v[2:3], v[58:59]
	v_mov_b64_e32 v[22:23], v[34:35]
	v_mov_b64_e32 v[4:5], v[60:61]
	v_mov_b64_e32 v[12:13], v[52:53]
	v_mov_b64_e32 v[6:7], v[62:63]
	v_mov_b64_e32 v[14:15], v[54:55]
	v_mov_b64_e32 v[26:27], v[46:47]
	v_mov_b64_e32 v[30:31], v[38:39]
	v_mov_b64_e32 v[20:21], v[44:45]
	v_mov_b64_e32 v[24:25], v[36:37]
	v_mov_b64_e32 v[8:9], v[64:65]
	v_mov_b64_e32 v[16:17], v[56:57]
	v_mov_b64_e32 v[28:29], v[48:49]
	v_mov_b64_e32 v[32:33], v[40:41]
	s_branch .LBB0_858
.LBB0_857:
	v_and_b32_e32 v111, 0xffff0000, v64
	v_and_b32_e32 v110, 0xffff0000, v62
	v_and_b32_e32 v115, 0xffff0000, v65
	v_and_b32_e32 v114, 0xffff0000, v63
	v_lshlrev_b32_e32 v109, 16, v64
	v_lshlrev_b32_e32 v108, 16, v62
	v_lshlrev_b32_e32 v113, 16, v65
	v_lshlrev_b32_e32 v112, 16, v63
	v_lshlrev_b32_e32 v84, 16, v34
	v_and_b32_e32 v85, 0xffff0000, v34
	v_lshlrev_b32_e32 v88, 16, v35
	v_and_b32_e32 v89, 0xffff0000, v35
	v_lshlrev_b32_e32 v74, 16, v36
	v_and_b32_e32 v75, 0xffff0000, v36
	v_lshlrev_b32_e32 v80, 16, v37
	v_and_b32_e32 v81, 0xffff0000, v37
	v_pk_mul_f32 v[34:35], v[110:111], v[110:111]
	v_pk_mul_f32 v[36:37], v[114:115], v[114:115]
	v_pk_fma_f32 v[34:35], v[108:109], v[108:109], v[34:35]
	v_pk_fma_f32 v[36:37], v[112:113], v[112:113], v[36:37]
	v_and_b32_e32 v95, 0xffff0000, v55
	v_and_b32_e32 v94, 0xffff0000, v54
	v_pk_add_f32 v[34:35], v[34:35], v[36:37]
	v_lshlrev_b32_e32 v93, 16, v55
	v_lshlrev_b32_e32 v92, 16, v54
	v_lshlrev_b32_e32 v96, 16, v56
	v_and_b32_e32 v97, 0xffff0000, v56
	v_lshlrev_b32_e32 v98, 16, v57
	v_lshlrev_b32_e32 v102, 16, v50
	v_and_b32_e32 v103, 0xffff0000, v50
	v_lshlrev_b32_e32 v50, 16, v46
	v_pk_add_f32 v[34:35], v[34:35], v[34:35] op_sel_hi:[0,1]
	v_pk_mul_f32 v[36:37], v[94:95], v[94:95]
	v_and_b32_e32 v99, 0xffff0000, v57
	v_lshlrev_b32_e32 v106, 16, v51
	v_and_b32_e32 v107, 0xffff0000, v51
	v_lshlrev_b32_e32 v82, 16, v38
	v_and_b32_e32 v83, 0xffff0000, v38
	v_lshlrev_b32_e32 v86, 16, v39
	v_and_b32_e32 v87, 0xffff0000, v39
	v_pk_fma_f32 v[36:37], v[92:93], v[92:93], v[36:37]
	v_mul_f32_e32 v51, v96, v96
; template <bool FINAL, bool DUMMY = false> __device__ __forceinline__ void norm_rows(const bfu* F, bfu* XB, const float* g1, float* RS, float* xout, int gw, int NGW, int lane, bfu* dummy = nullptr) {
;     ...
;     for (; m < M; m += NGW) {
;         f32x4 f[8], x[8]; float s = 0.f;
; #pragma unroll
;         for (int j = 0; j < 4; ++j) {
;             f[2 * j] = (f32x4){bflo(fw[j].x), bfhi(fw[j].x), bflo(fw[j].y), bfhi(fw[j].y)}; f[2 * j + 1] = (f32x4){bflo(fw[j].z), bfhi(fw[j].z), bflo(fw[j].w), bfhi(fw[j].w)};
;             x[2 * j] = (f32x4){bflo(xw[j].x), bfhi(xw[j].x), bflo(xw[j].y), bfhi(xw[j].y)}; x[2 * j + 1] = (f32x4){bflo(xw[j].z), bfhi(xw[j].z), bflo(xw[j].w), bfhi(xw[j].w)}; }
;         const int mn = m + NGW;
;         if (mn < M) {
; #pragma unroll
;             for (int j = 0; j < 4; ++j) { fw[j] = __builtin_nontemporal_load((const v4u*)(F + (size_t)mn * DM) + lane + 64 * j); xw[j] = ((const v4u*)(XB + (size_t)mn * DM) + lane)[64 * j]; }
;         }
; #pragma unroll
;         for (int k = 0; k < 8; ++k) s += (f[k].x * f[k].x + f[k].y * f[k].y) + (f[k].z * f[k].z + f[k].w * f[k].w);
;         const float rstd1 = 1.f / sqrtf(wave_sum(s) * (1.f / DM) + EPS);
;         float s2 = 0.f;
; #pragma unroll
;         for (int k = 0; k < 8; ++k) { const f32x4 gg = ((const f32x4*)g1)[2 * lane + 128 * (k >> 1) + (k & 1)]; x[k] = x[k] + f[k] * rstd1 * gg; s2 += (x[k].x * x[k].x + x[k].y * x[k].y) + (x[k].z * x[k].z + x[k].w * x[k].w); }
	v_mul_f32_e32 v39, v97, v97
	v_mul_f32_e32 v34, v98, v98
	v_mov_b32_e32 v38, v50
	v_lshlrev_b32_e32 v100, 16, v52
	v_and_b32_e32 v101, 0xffff0000, v52
	v_lshlrev_b32_e32 v104, 16, v53
	v_and_b32_e32 v105, 0xffff0000, v53
	v_and_b32_e32 v130, 0xffff0000, v46
	v_lshlrev_b32_e32 v52, 16, v47
	v_and_b32_e32 v53, 0xffff0000, v47
	v_lshlrev_b32_e32 v78, 16, v40
	v_and_b32_e32 v129, 0xffff0000, v40
	v_lshlrev_b32_e32 v76, 16, v41
	v_and_b32_e32 v77, 0xffff0000, v41
	v_pk_add_f32 v[36:37], v[36:37], v[36:37] op_sel_hi:[0,1]
	v_pk_fma_f32 v[40:41], v[98:99], v[98:99], v[34:35] op_sel_hi:[1,1,0]
	v_pk_add_f32 v[38:39], v[50:51], v[38:39]
	v_lshlrev_b32_e32 v62, 16, v42
	v_and_b32_e32 v63, 0xffff0000, v42
	v_lshlrev_b32_e32 v64, 16, v43
	v_and_b32_e32 v65, 0xffff0000, v43
	v_mul_f32_e32 v40, v130, v130
	v_mul_f32_e32 v34, v52, v52
	v_mul_f32_e32 v36, v53, v53
	v_mul_f32_e32 v42, v50, v50
	v_mov_b32_e32 v43, v39
	v_pk_add_f32 v[38:39], v[42:43], v[40:41]
	v_pk_add_f32 v[34:35], v[34:35], v[36:37]
	v_and_b32_e32 v57, 0xffff0000, v49
	v_and_b32_e32 v56, 0xffff0000, v48
	v_pk_add_f32 v[34:35], v[38:39], v[34:35]
	v_lshlrev_b32_e32 v55, 16, v49
	v_lshlrev_b32_e32 v54, 16, v48
	v_pk_add_f32 v[34:35], v[34:35], v[34:35] op_sel_hi:[0,1]
	v_pk_mul_f32 v[36:37], v[56:57], v[56:57]
	v_mul_f32_e32 v79, v82, v82
	v_pk_fma_f32 v[36:37], v[54:55], v[54:55], v[36:37]
	v_mul_f32_e32 v39, v83, v83
	v_mul_f32_e32 v34, v86, v86
	v_mov_b32_e32 v38, v78
	v_pk_add_f32 v[36:37], v[36:37], v[36:37] op_sel_hi:[0,1]
	v_pk_fma_f32 v[40:41], v[86:87], v[86:87], v[34:35] op_sel_hi:[1,1,0]
	v_pk_add_f32 v[38:39], v[78:79], v[38:39]
	v_mul_f32_e32 v40, v129, v129
	v_mul_f32_e32 v36, v76, v76
	v_mul_f32_e32 v34, v77, v77
	v_mul_f32_e32 v42, v78, v78
	v_mov_b32_e32 v43, v39
	v_pk_add_f32 v[38:39], v[42:43], v[40:41]
	v_pk_add_f32 v[34:35], v[36:37], v[34:35]
	v_lshlrev_b32_e32 v118, 16, v58
	v_pk_add_f32 v[34:35], v[38:39], v[34:35]
	v_and_b32_e32 v119, 0xffff0000, v58
	v_add_f32_e32 v34, v34, v35
	v_lshlrev_b32_e32 v122, 16, v59
	v_and_b32_e32 v123, 0xffff0000, v59
	v_lshlrev_b32_e32 v116, 16, v60
	v_and_b32_e32 v117, 0xffff0000, v60
	s_waitcnt lgkmcnt(0)
	s_nop 1
	v_add_f32_dpp v34, v34, v34 quad_perm:[1,0,3,2] row_mask:0xf bank_mask:0xf
	v_lshlrev_b32_e32 v120, 16, v61
	v_and_b32_e32 v121, 0xffff0000, v61
	v_lshlrev_b32_e32 v58, 16, v44
	v_and_b32_e32 v59, 0xffff0000, v44
	s_nop 1
	v_add_f32_dpp v34, v34, v34 quad_perm:[2,3,0,1] row_mask:0xf bank_mask:0xf
	v_lshlrev_b32_e32 v60, 16, v45
	v_and_b32_e32 v61, 0xffff0000, v45
	v_mov_b32_e32 v42, v108
	v_mov_b32_e32 v43, v110
	s_nop 1
	v_add_f32_dpp v34, v34, v34 row_half_mirror row_mask:0xf bank_mask:0xf
	v_mov_b32_e32 v44, v112
	v_mov_b32_e32 v45, v114
	v_mov_b32_e32 v110, v109
	v_mov_b32_e32 v114, v113
	s_nop 1
	v_add_f32_dpp v34, v34, v34 row_mirror row_mask:0xf bank_mask:0xf
	v_mov_b32_e32 v109, v94
	v_mov_b32_e32 v94, v93
	v_mov_b32_e32 v108, v92
	v_mov_b32_e32 v51, v130
	v_mov_b32_e32 v35, v34
	s_nop 1
	v_permlane16_swap_b32_e32 v34, v35
	v_add_f32_e32 v34, v34, v35
	v_mov_b32_e32 v79, v129
	s_add_u32 s36, s36, 0x20000
	s_addc_u32 s37, s37, 0
	s_add_u32 s40, s40, 0x20000
	v_mov_b32_e32 v35, v34
	s_nop 1
	v_permlane32_swap_b32_e32 v34, v35
	v_add_f32_e32 v34, v34, v35
	v_fmamk_f32 v34, v34, 0x3a000000, v236
	v_cmp_gt_f32_e32 vcc, s68, v34
	v_mul_f32_e32 v35, 0x4f800000, v34
	s_addc_u32 s41, s41, 0
	v_cndmask_b32_e32 v34, v34, v35, vcc
	v_sqrt_f32_e32 v35, v34
	s_nop 0
	v_add_u32_e32 v36, -1, v35
	v_fma_f32 v37, -v36, v35, v34
	v_cmp_ge_f32_e64 s[38:39], 0, v37
	v_add_u32_e32 v37, 1, v35
	s_nop 0
	v_cndmask_b32_e64 v36, v35, v36, s[38:39]
	v_fma_f32 v35, -v37, v35, v34
	v_cmp_lt_f32_e64 s[38:39], 0, v35
	s_nop 1
	v_cndmask_b32_e64 v35, v36, v37, s[38:39]
	v_mul_f32_e32 v36, 0x37800000, v35
	v_cndmask_b32_e32 v35, v35, v36, vcc
	v_cmp_class_f32_e32 vcc, v34, v234
	s_nop 1
	v_cndmask_b32_e32 v34, v35, v34, vcc
	v_div_scale_f32 v35, s[22:23], v34, v34, 1.0
	v_rcp_f32_e32 v36, v35
	v_readlane_b32 s22, v255, 45
	v_readlane_b32 s23, v255, 46
	v_fma_f32 v37, -v35, v36, 1.0
	v_fmac_f32_e32 v36, v37, v36
	v_div_scale_f32 v37, vcc, 1.0, v34, 1.0
	v_mul_f32_e32 v38, v37, v36
	v_fma_f32 v39, -v35, v38, v37
	v_fmac_f32_e32 v38, v39, v36
	v_fma_f32 v35, -v35, v38, v37
	v_div_fmas_f32 v35, v35, v36, v38
	v_div_fixup_f32 v90, v35, v34, 1.0
	global_load_dwordx4 v[38:41], v[66:67], off offset:16
	global_load_dwordx4 v[34:37], v[66:67], off
	v_pk_mul_f32 v[42:43], v[90:91], v[42:43] op_sel_hi:[0,1]
	v_pk_mul_f32 v[44:45], v[90:91], v[44:45] op_sel_hi:[0,1]
	v_pk_mul_f32 v[92:93], v[90:91], v[94:95] op_sel_hi:[0,1]
	v_pk_mul_f32 v[94:95], v[90:91], v[98:99] op_sel_hi:[0,1]
	v_pk_mul_f32 v[50:51], v[90:91], v[50:51] op_sel_hi:[0,1]
	v_pk_mul_f32 v[52:53], v[90:91], v[52:53] op_sel_hi:[0,1]
	v_pk_mul_f32 v[108:109], v[90:91], v[108:109] op_sel_hi:[0,1]
	v_pk_mul_f32 v[82:83], v[90:91], v[82:83] op_sel_hi:[0,1]
	v_pk_mul_f32 v[86:87], v[90:91], v[86:87] op_sel_hi:[0,1]
	v_pk_mul_f32 v[78:79], v[90:91], v[78:79] op_sel_hi:[0,1]
	v_pk_mul_f32 v[76:77], v[90:91], v[76:77] op_sel_hi:[0,1]
	s_and_b64 vcc, exec, s[42:43]
	s_waitcnt vmcnt(0)
; template <bool FINAL, bool DUMMY = false> __device__ __forceinline__ void norm_rows(const bfu* F, bfu* XB, const float* g1, float* RS, float* xout, int gw, int NGW, int lane, bfu* dummy = nullptr) {
;     ...
;         for (int k = 0; k < 8; ++k) { const f32x4 gg = ((const f32x4*)g1)[2 * lane + 128 * (k >> 1) + (k & 1)]; x[k] = x[k] + f[k] * rstd1 * gg; s2 += (x[k].x * x[k].x + x[k].y * x[k].y) + (x[k].z * x[k].z + x[k].w * x[k].w); }
;         if (FINAL) { f32x4* xo = (f32x4*)(xout + (size_t)m * DM);
; #pragma unroll
;             for (int k = 0; k < 8; ++k) __builtin_nontemporal_store(x[k], xo + 2 * lane + 128 * (k >> 1) + (k & 1));
	v_pk_fma_f32 v[36:37], v[36:37], v[44:45], v[122:123]
	v_pk_fma_f32 v[34:35], v[34:35], v[42:43], v[118:119]
	v_pk_mul_f32 v[42:43], v[90:91], v[110:111] op_sel_hi:[0,1]
	v_pk_mul_f32 v[44:45], v[90:91], v[114:115] op_sel_hi:[0,1]
	v_pk_fma_f32 v[40:41], v[40:41], v[44:45], v[120:121]
	v_pk_fma_f32 v[38:39], v[38:39], v[42:43], v[116:117]
	global_load_dwordx4 v[42:45], v[66:67], off offset:2064
	global_load_dwordx4 v[46:49], v[66:67], off offset:2048
	s_waitcnt vmcnt(1)
	v_pk_fma_f32 v[44:45], v[44:45], v[94:95], v[104:105]
	s_waitcnt vmcnt(0)
	v_pk_fma_f32 v[48:49], v[48:49], v[92:93], v[106:107]
	v_pk_mul_f32 v[92:93], v[90:91], v[96:97] op_sel_hi:[0,1]
	v_pk_fma_f32 v[42:43], v[42:43], v[92:93], v[100:101]
	global_load_dwordx4 v[92:95], v[68:69], off offset:16
	global_load_dwordx4 v[96:99], v[68:69], off
	v_pk_fma_f32 v[46:47], v[46:47], v[108:109], v[102:103]
	s_waitcnt vmcnt(0)
	v_pk_fma_f32 v[50:51], v[96:97], v[50:51], v[62:63]
	v_mov_b32_e32 v62, v54
	v_mov_b32_e32 v63, v56
	v_mov_b32_e32 v56, v55
	v_pk_mul_f32 v[62:63], v[90:91], v[62:63] op_sel_hi:[0,1]
	v_pk_mul_f32 v[54:55], v[90:91], v[56:57] op_sel_hi:[0,1]
	v_pk_fma_f32 v[52:53], v[98:99], v[52:53], v[64:65]
	v_pk_fma_f32 v[56:57], v[94:95], v[54:55], v[60:61]
	v_pk_fma_f32 v[54:55], v[92:93], v[62:63], v[58:59]
	global_load_dwordx4 v[58:61], v[70:71], off offset:16
	global_load_dwordx4 v[62:65], v[70:71], off
	s_waitcnt vmcnt(1)
	v_pk_fma_f32 v[60:61], v[60:61], v[76:77], v[80:81]
	s_waitcnt vmcnt(0)
	v_pk_fma_f32 v[64:65], v[64:65], v[86:87], v[88:89]
	v_pk_fma_f32 v[62:63], v[62:63], v[82:83], v[84:85]
	v_pk_fma_f32 v[58:59], v[58:59], v[78:79], v[74:75]
	global_store_dwordx4 v[72:73], v[34:37], off offset:-4096 nt
	global_store_dwordx4 v[72:73], v[38:41], off offset:-4080 nt
	global_store_dwordx4 v[72:73], v[46:49], off offset:-2048 nt
	global_store_dwordx4 v[72:73], v[42:45], off offset:-2032 nt
	global_store_dwordx4 v[72:73], v[50:53], off nt
	global_store_dwordx4 v[72:73], v[54:57], off offset:16 nt
	global_store_dwordx4 v[72:73], v[62:65], off offset:2048 nt
	global_store_dwordx4 v[72:73], v[58:61], off offset:2064 nt
	v_mov_b64_e32 v[52:53], v[12:13]
	v_mov_b64_e32 v[44:45], v[20:21]
	v_mov_b64_e32 v[60:61], v[4:5]
	v_mov_b64_e32 v[36:37], v[24:25]
	v_mov_b64_e32 v[64:65], v[8:9]
	v_mov_b64_e32 v[56:57], v[16:17]
	v_mov_b64_e32 v[48:49], v[28:29]
	v_mov_b64_e32 v[40:41], v[32:33]
	v_lshl_add_u64 v[72:73], v[72:73], 0, s[22:23]
	v_mov_b64_e32 v[58:59], v[2:3]
	v_mov_b64_e32 v[50:51], v[10:11]
	v_mov_b64_e32 v[42:43], v[18:19]
	v_mov_b64_e32 v[34:35], v[22:23]
	v_mov_b64_e32 v[62:63], v[6:7]
	v_mov_b64_e32 v[54:55], v[14:15]
	v_mov_b64_e32 v[46:47], v[26:27]
	v_mov_b64_e32 v[38:39], v[30:31]
	s_cbranch_vccnz .LBB0_860
